# P2 epilogue stores sc1 nt
# speedup vs baseline: 1.0710x; 1.0710x over previous
; __device__ __forceinline__ unsigned cvt_pk_bf16(float lo, float hi) { unsigned r; asm volatile("v_cvt_pk_bf16_f32 %0, %1, %2" : "=v"(r) : "v"(lo), "v"(hi)); return r; }
;     __device__ __forceinline__ void operator()(const f32x4 (&acc)[2][2][4][2], const Unit& u, int wr, int wc, int fr, int fq) const {
;     ...
;             bf16_t* base; int ld, ct; float sc = 1.f;
;             if (pn < 4) { base = Q; ld = 1024; ct = pn; sc = qscale; } else if (pn < 8) { base = Kb; ld = 1024; ct = pn - 4; } else if (pn < 12) { base = V; ld = 1024; ct = pn - 8; }
;             else if (pn < 14) { base = U; ld = 512; ct = pn - 12; } else { base = G; ld = 2048; ct = pn - 14; }
;             const int row0 = u.pm * BM + wr * 64 + fr, col0 = ct * 256 + wc * 32 + 8 * fq;
; #pragma unroll
;             for (int ai = 0; ai < 2; ++ai)
; #pragma unroll
;                 for (int m = 0; m < 4; ++m) { bf16_t* rowp = base + (size_t)(row0 + ai * HALF + m * 16) * ld + col0;
; #pragma unroll
;                     for (int bj = 0; bj < 2; ++bj) { const f32x4 v0 = acc[ai][bj][m][0] * sc, v1 = acc[ai][bj][m][1] * sc;
;                         u32x4 w; w.x = cvt_pk_bf16(v0[0], v0[1]); w.y = cvt_pk_bf16(v0[2], v0[3]); w.z = cvt_pk_bf16(v1[0], v1[1]); w.w = cvt_pk_bf16(v1[2], v1[3]);
;                         __builtin_nontemporal_store(w, (u32x4*)(rowp + bj * HALF)); } }
.LBB0_215:
	s_cmp_lt_u32 s73, 14
	s_cselect_b64 s[60:61], -1, 0
	s_and_b64 s[66:67], s[60:61], exec
	s_cselect_b32 s13, -12, -14
	s_add_i32 s13, s13, s73
	s_and_b64 s[60:61], s[60:61], exec
	s_cselect_b32 s15, s1, s21
	s_cselect_b32 s33, s0, s20
	v_lshl_add_u32 v148, s58, 8, v150
	v_mov_b32_e32 v146, s33
	s_waitcnt lgkmcnt(0)
	v_mov_b32_e32 v147, s15
	v_lshl_or_b32 v162, s13, 8, v158
	v_mov_b32_e32 v163, v137
	v_ashrrev_i32_e32 v149, 31, v148
	s_cselect_b32 s13, 9, 11
	v_lshl_add_u64 v[146:147], v[162:163], 1, v[146:147]
	v_lshlrev_b64 v[162:163], s13, v[148:149]
	v_lshl_add_u64 v[166:167], v[162:163], 1, v[146:147]
	v_cvt_pk_bf16_f32 v162, v124, v125
	v_cvt_pk_bf16_f32 v163, v126, v127
	v_cvt_pk_bf16_f32 v164, v120, v121
	v_cvt_pk_bf16_f32 v165, v122, v123
	global_store_dwordx4 v[166:167], v[162:165], off sc1 nt
	s_nop 1
	v_cvt_pk_bf16_f32 v162, v68, v69
	v_cvt_pk_bf16_f32 v163, v70, v71
	v_cvt_pk_bf16_f32 v164, v64, v65
	v_cvt_pk_bf16_f32 v165, v66, v67
	global_store_dwordx4 v[166:167], v[162:165], off offset:256 sc1 nt
	s_nop 1
	v_or_b32_e32 v162, 16, v148
	v_ashrrev_i32_e32 v163, 31, v162
	v_lshlrev_b64 v[162:163], s13, v[162:163]
	v_lshl_add_u64 v[166:167], v[162:163], 1, v[146:147]
	v_cvt_pk_bf16_f32 v162, v116, v117
	v_cvt_pk_bf16_f32 v163, v118, v119
	v_cvt_pk_bf16_f32 v164, v112, v113
	v_cvt_pk_bf16_f32 v165, v114, v115
	global_store_dwordx4 v[166:167], v[162:165], off sc1 nt
	s_nop 1
	v_cvt_pk_bf16_f32 v162, v56, v57
	v_cvt_pk_bf16_f32 v163, v58, v59
	v_cvt_pk_bf16_f32 v164, v48, v49
	v_cvt_pk_bf16_f32 v165, v50, v51
	global_store_dwordx4 v[166:167], v[162:165], off offset:256 sc1 nt
	s_nop 1
	v_or_b32_e32 v162, 32, v148
	v_ashrrev_i32_e32 v163, 31, v162
	v_lshlrev_b64 v[162:163], s13, v[162:163]
	v_lshl_add_u64 v[166:167], v[162:163], 1, v[146:147]
	v_cvt_pk_bf16_f32 v162, v108, v109
	v_cvt_pk_bf16_f32 v163, v110, v111
	v_cvt_pk_bf16_f32 v164, v104, v105
	v_cvt_pk_bf16_f32 v165, v106, v107
	global_store_dwordx4 v[166:167], v[162:165], off sc1 nt
	s_nop 1
	v_cvt_pk_bf16_f32 v162, v44, v45
	v_cvt_pk_bf16_f32 v163, v46, v47
	v_cvt_pk_bf16_f32 v164, v40, v41
	v_cvt_pk_bf16_f32 v165, v42, v43
	global_store_dwordx4 v[166:167], v[162:165], off offset:256 sc1 nt
	s_nop 1
	v_or_b32_e32 v162, 48, v148
	v_ashrrev_i32_e32 v163, 31, v162
	v_lshlrev_b64 v[162:163], s13, v[162:163]
	v_lshl_add_u64 v[166:167], v[162:163], 1, v[146:147]
	v_cvt_pk_bf16_f32 v162, v100, v101
	v_cvt_pk_bf16_f32 v163, v102, v103
	v_cvt_pk_bf16_f32 v164, v96, v97
	v_cvt_pk_bf16_f32 v165, v98, v99
	global_store_dwordx4 v[166:167], v[162:165], off sc1 nt
	s_nop 1
	v_cvt_pk_bf16_f32 v162, v36, v37
	v_cvt_pk_bf16_f32 v163, v38, v39
	v_cvt_pk_bf16_f32 v164, v32, v33
	v_cvt_pk_bf16_f32 v165, v34, v35
	global_store_dwordx4 v[166:167], v[162:165], off offset:256 sc1 nt
	s_nop 1
	v_add_u32_e32 v162, 0x80, v148
	v_ashrrev_i32_e32 v163, 31, v162
	v_lshlrev_b64 v[162:163], s13, v[162:163]
	v_lshl_add_u64 v[166:167], v[162:163], 1, v[146:147]
	v_cvt_pk_bf16_f32 v162, v92, v93
	v_cvt_pk_bf16_f32 v163, v94, v95
	v_cvt_pk_bf16_f32 v164, v88, v89
	v_cvt_pk_bf16_f32 v165, v90, v91
	global_store_dwordx4 v[166:167], v[162:165], off sc1 nt
	s_nop 1
	v_cvt_pk_bf16_f32 v162, v28, v29
	v_cvt_pk_bf16_f32 v163, v30, v31
	v_cvt_pk_bf16_f32 v164, v24, v25
	v_cvt_pk_bf16_f32 v165, v26, v27
	global_store_dwordx4 v[166:167], v[162:165], off offset:256 sc1 nt
	s_nop 1
	v_add_u32_e32 v162, 0x90, v148
	v_ashrrev_i32_e32 v163, 31, v162
	v_lshlrev_b64 v[162:163], s13, v[162:163]
	v_lshl_add_u64 v[166:167], v[162:163], 1, v[146:147]
	v_cvt_pk_bf16_f32 v162, v84, v85
	v_cvt_pk_bf16_f32 v163, v86, v87
	v_cvt_pk_bf16_f32 v164, v80, v81
	v_cvt_pk_bf16_f32 v165, v82, v83
	global_store_dwordx4 v[166:167], v[162:165], off sc1 nt
	s_nop 1
	v_cvt_pk_bf16_f32 v162, v20, v21
	v_cvt_pk_bf16_f32 v163, v22, v23
	v_cvt_pk_bf16_f32 v164, v16, v17
	v_cvt_pk_bf16_f32 v165, v18, v19
	global_store_dwordx4 v[166:167], v[162:165], off offset:256 sc1 nt
	s_nop 1
	v_add_u32_e32 v162, 0xa0, v148
	v_ashrrev_i32_e32 v163, 31, v162
	v_lshlrev_b64 v[162:163], s13, v[162:163]
	v_add_u32_e32 v148, 0xb0, v148
	v_lshl_add_u64 v[166:167], v[162:163], 1, v[146:147]
	v_cvt_pk_bf16_f32 v162, v76, v77
	v_cvt_pk_bf16_f32 v163, v78, v79
	v_ashrrev_i32_e32 v149, 31, v148
	v_cvt_pk_bf16_f32 v164, v72, v73
	v_cvt_pk_bf16_f32 v165, v74, v75
	global_store_dwordx4 v[166:167], v[162:165], off sc1 nt
	v_lshlrev_b64 v[148:149], s13, v[148:149]
	s_nop 0
	v_cvt_pk_bf16_f32 v162, v12, v13
	v_cvt_pk_bf16_f32 v163, v14, v15
	v_cvt_pk_bf16_f32 v164, v8, v9
	v_cvt_pk_bf16_f32 v165, v10, v11
	global_store_dwordx4 v[166:167], v[162:165], off offset:256 sc1 nt
	s_nop 1
	v_lshl_add_u64 v[162:163], v[148:149], 1, v[146:147]
	v_cvt_pk_bf16_f32 v146, v60, v61
	v_cvt_pk_bf16_f32 v147, v62, v63
	v_cvt_pk_bf16_f32 v148, v52, v53
	v_cvt_pk_bf16_f32 v149, v54, v55
	global_store_dwordx4 v[162:163], v[146:149], off sc1 nt
	s_nop 1
	v_cvt_pk_bf16_f32 v146, v4, v5
	v_cvt_pk_bf16_f32 v147, v6, v7
	v_cvt_pk_bf16_f32 v148, v0, v1
	v_cvt_pk_bf16_f32 v149, v2, v3
	global_store_dwordx4 v[162:163], v[146:149], off offset:256 sc1 nt
	s_cbranch_execnz .LBB0_202

; __device__ __forceinline__ unsigned cvt_pk_bf16(float lo, float hi) { unsigned r; asm volatile("v_cvt_pk_bf16_f32 %0, %1, %2" : "=v"(r) : "v"(lo), "v"(hi)); return r; }
;     __device__ __forceinline__ void operator()(const f32x4 (&acc)[2][2][4][2], const Unit& u, int wr, int wc, int fr, int fq) const {
;     ...
;         if (HEADMAJOR && pn < 12) {
;             bf16_t* base; int ct; float sc = 1.f;
;             if (pn < 4) { base = Q; ct = pn; sc = qscale; } else if (pn < 8) { base = Kb; ct = pn - 4; } else { base = V; ct = pn - 8; }
;             const int b = u.pm >> 3, t0 = (u.pm & 7) * BM + wr * 64 + fr;
; #pragma unroll
;             for (int bj = 0; bj < 2; ++bj) { bf16_t* hb = base + ((size_t)((b * 8 + 2 * ct + bj) * 2048 + t0)) * 128 + wc * 32 + 8 * fq;
; #pragma unroll
;                 for (int ai = 0; ai < 2; ++ai)
; #pragma unroll
;                     for (int m = 0; m < 4; ++m) { const f32x4 v0 = acc[ai][bj][m][0] * sc, v1 = acc[ai][bj][m][1] * sc;
;                         u32x4 w; w.x = cvt_pk_bf16(v0[0], v0[1]); w.y = cvt_pk_bf16(v0[2], v0[3]); w.z = cvt_pk_bf16(v1[0], v1[1]); w.w = cvt_pk_bf16(v1[2], v1[3]);
;                         __builtin_nontemporal_store(w, (u32x4*)(hb + (ai * HALF + m * 16) * 128)); } }
.LBB0_223:
	s_lshl_b32 s13, s58, 8
	s_and_b32 s13, s13, 0x700
	s_add_u32 s66, s66, s22
	s_addc_u32 s67, s67, 0
	s_lshl_b32 s33, s58, 11
	s_lshl_b32 s15, s73, 12
	s_and_b32 s33, s33, 0xffffc000
	s_add_i32 s15, s15, s33
	s_or_b32 s13, s15, s13
	v_add_u32_e32 v148, s13, v150
	v_ashrrev_i32_e32 v149, 31, v148
	s_waitcnt lgkmcnt(0)
	v_lshl_add_u64 v[146:147], s[66:67], 0, v[136:137]
	v_lshlrev_b64 v[162:163], 8, v[148:149]
	v_lshl_add_u64 v[162:163], v[146:147], 0, v[162:163]
	v_pk_mul_f32 v[126:127], v[126:127], s[60:61] op_sel_hi:[1,0]
	v_pk_mul_f32 v[124:125], v[124:125], s[60:61] op_sel_hi:[1,0]
	v_pk_mul_f32 v[164:165], v[122:123], s[60:61] op_sel_hi:[1,0]
	v_pk_mul_f32 v[122:123], v[120:121], s[60:61] op_sel_hi:[1,0]
	v_cvt_pk_bf16_f32 v120, v124, v125
	v_cvt_pk_bf16_f32 v121, v126, v127
	v_pk_mul_f32 v[116:117], v[116:117], s[60:61] op_sel_hi:[1,0]
	v_cvt_pk_bf16_f32 v122, v122, v123
	v_cvt_pk_bf16_f32 v123, v164, v165
	global_store_dwordx4 v[162:163], v[120:123], off sc1 nt
	v_pk_mul_f32 v[118:119], v[118:119], s[60:61] op_sel_hi:[1,0]
	v_pk_mul_f32 v[110:111], v[110:111], s[60:61] op_sel_hi:[1,0]
	v_pk_mul_f32 v[120:121], v[114:115], s[60:61] op_sel_hi:[1,0]
	v_pk_mul_f32 v[114:115], v[112:113], s[60:61] op_sel_hi:[1,0]
	v_cvt_pk_bf16_f32 v112, v116, v117
	v_add_co_u32_e32 v116, vcc, s89, v162
	v_cvt_pk_bf16_f32 v113, v118, v119
	v_cvt_pk_bf16_f32 v114, v114, v115
	v_cvt_pk_bf16_f32 v115, v120, v121
	v_pk_mul_f32 v[108:109], v[108:109], s[60:61] op_sel_hi:[1,0]
	s_nop 0
	v_addc_co_u32_e32 v117, vcc, 0, v163, vcc
	global_store_dwordx4 v[116:117], v[112:115], off offset:-4096 sc1 nt
	v_pk_mul_f32 v[100:101], v[100:101], s[60:61] op_sel_hi:[1,0]
	v_pk_mul_f32 v[102:103], v[102:103], s[60:61] op_sel_hi:[1,0]
	v_pk_mul_f32 v[112:113], v[106:107], s[60:61] op_sel_hi:[1,0]
	v_pk_mul_f32 v[106:107], v[104:105], s[60:61] op_sel_hi:[1,0]
	v_cvt_pk_bf16_f32 v104, v108, v109
	v_cvt_pk_bf16_f32 v105, v110, v111
	v_pk_mul_f32 v[92:93], v[92:93], s[60:61] op_sel_hi:[1,0]
	v_cvt_pk_bf16_f32 v106, v106, v107
	v_cvt_pk_bf16_f32 v107, v112, v113
	global_store_dwordx4 v[116:117], v[104:107], off sc1 nt
	v_pk_mul_f32 v[94:95], v[94:95], s[60:61] op_sel_hi:[1,0]
	v_pk_mul_f32 v[86:87], v[86:87], s[60:61] op_sel_hi:[1,0]
	v_pk_mul_f32 v[104:105], v[98:99], s[60:61] op_sel_hi:[1,0]
	v_pk_mul_f32 v[98:99], v[96:97], s[60:61] op_sel_hi:[1,0]
	v_cvt_pk_bf16_f32 v96, v100, v101
	v_add_co_u32_e32 v100, vcc, s23, v162
	v_cvt_pk_bf16_f32 v97, v102, v103
	v_cvt_pk_bf16_f32 v98, v98, v99
	v_cvt_pk_bf16_f32 v99, v104, v105
	v_pk_mul_f32 v[84:85], v[84:85], s[60:61] op_sel_hi:[1,0]
	s_nop 0
	v_addc_co_u32_e32 v101, vcc, 0, v163, vcc
	global_store_dwordx4 v[100:101], v[96:99], off sc1 nt
	v_pk_mul_f32 v[76:77], v[76:77], s[60:61] op_sel_hi:[1,0]
	s_mov_b32 s13, 0xb000
	v_pk_mul_f32 v[96:97], v[90:91], s[60:61] op_sel_hi:[1,0]
	v_pk_mul_f32 v[90:91], v[88:89], s[60:61] op_sel_hi:[1,0]
	v_cvt_pk_bf16_f32 v88, v92, v93
	v_add_co_u32_e32 v92, vcc, s72, v162
	v_cvt_pk_bf16_f32 v89, v94, v95
	v_cvt_pk_bf16_f32 v90, v90, v91
	v_cvt_pk_bf16_f32 v91, v96, v97
	v_pk_mul_f32 v[78:79], v[78:79], s[60:61] op_sel_hi:[1,0]
	s_nop 0
	v_addc_co_u32_e32 v93, vcc, 0, v163, vcc
	global_store_dwordx4 v[92:93], v[88:91], off offset:-4096 sc1 nt
	v_pk_mul_f32 v[60:61], v[60:61], s[60:61] op_sel_hi:[1,0]
	v_pk_mul_f32 v[62:63], v[62:63], s[60:61] op_sel_hi:[1,0]
	v_pk_mul_f32 v[88:89], v[82:83], s[60:61] op_sel_hi:[1,0]
	v_pk_mul_f32 v[82:83], v[80:81], s[60:61] op_sel_hi:[1,0]
	v_cvt_pk_bf16_f32 v80, v84, v85
	v_cvt_pk_bf16_f32 v81, v86, v87
	v_pk_mul_f32 v[64:65], v[64:65], s[60:61] op_sel_hi:[1,0]
	v_cvt_pk_bf16_f32 v82, v82, v83
	v_cvt_pk_bf16_f32 v83, v88, v89
	global_store_dwordx4 v[92:93], v[80:83], off sc1 nt
	v_pk_mul_f32 v[46:47], v[46:47], s[60:61] op_sel_hi:[1,0]
	v_pk_mul_f32 v[44:45], v[44:45], s[60:61] op_sel_hi:[1,0]
	v_pk_mul_f32 v[80:81], v[74:75], s[60:61] op_sel_hi:[1,0]
	v_pk_mul_f32 v[74:75], v[72:73], s[60:61] op_sel_hi:[1,0]
	v_cvt_pk_bf16_f32 v72, v76, v77
	v_add_co_u32_e32 v76, vcc, s13, v162
	v_cvt_pk_bf16_f32 v73, v78, v79
	v_cvt_pk_bf16_f32 v74, v74, v75
	v_cvt_pk_bf16_f32 v75, v80, v81
	v_pk_mul_f32 v[36:37], v[36:37], s[60:61] op_sel_hi:[1,0]
	s_nop 0
	v_addc_co_u32_e32 v77, vcc, 0, v163, vcc
; __device__ __forceinline__ unsigned cvt_pk_bf16(float lo, float hi) { unsigned r; asm volatile("v_cvt_pk_bf16_f32 %0, %1, %2" : "=v"(r) : "v"(lo), "v"(hi)); return r; }
;     __device__ __forceinline__ void operator()(const f32x4 (&acc)[2][2][4][2], const Unit& u, int wr, int wc, int fr, int fq) const {
;     ...
;                     for (int m = 0; m < 4; ++m) { const f32x4 v0 = acc[ai][bj][m][0] * sc, v1 = acc[ai][bj][m][1] * sc;
;                         u32x4 w; w.x = cvt_pk_bf16(v0[0], v0[1]); w.y = cvt_pk_bf16(v0[2], v0[3]); w.z = cvt_pk_bf16(v1[0], v1[1]); w.w = cvt_pk_bf16(v1[2], v1[3]);
;                         __builtin_nontemporal_store(w, (u32x4*)(hb + (ai * HALF + m * 16) * 128)); } }
	global_store_dwordx4 v[76:77], v[72:75], off offset:-4096 sc1 nt
	v_pk_mul_f32 v[38:39], v[38:39], s[60:61] op_sel_hi:[1,0]
	v_pk_mul_f32 v[28:29], v[28:29], s[60:61] op_sel_hi:[1,0]
	v_pk_mul_f32 v[72:73], v[54:55], s[60:61] op_sel_hi:[1,0]
	v_pk_mul_f32 v[54:55], v[52:53], s[60:61] op_sel_hi:[1,0]
	v_cvt_pk_bf16_f32 v52, v60, v61
	v_cvt_pk_bf16_f32 v53, v62, v63
	v_pk_mul_f32 v[62:63], v[66:67], s[60:61] op_sel_hi:[1,0]
	v_cvt_pk_bf16_f32 v54, v54, v55
	v_cvt_pk_bf16_f32 v55, v72, v73
	global_store_dwordx4 v[76:77], v[52:55], off sc1 nt
	v_pk_mul_f32 v[30:31], v[30:31], s[60:61] op_sel_hi:[1,0]
	v_pk_mul_f32 v[22:23], v[22:23], s[60:61] op_sel_hi:[1,0]
	v_add_u32_e32 v52, 0x800, v148
	v_ashrrev_i32_e32 v53, 31, v52
	v_lshlrev_b64 v[52:53], 8, v[52:53]
	v_lshl_add_u64 v[60:61], v[146:147], 0, v[52:53]
	v_pk_mul_f32 v[52:53], v[68:69], s[60:61] op_sel_hi:[1,0]
	v_pk_mul_f32 v[54:55], v[70:71], s[60:61] op_sel_hi:[1,0]
	v_cvt_pk_bf16_f32 v52, v52, v53
	v_pk_mul_f32 v[20:21], v[20:21], s[60:61] op_sel_hi:[1,0]
	v_cvt_pk_bf16_f32 v53, v54, v55
	v_cvt_pk_bf16_f32 v54, v64, v65
	v_cvt_pk_bf16_f32 v55, v62, v63
	global_store_dwordx4 v[60:61], v[52:55], off sc1 nt
	v_pk_mul_f32 v[12:13], v[12:13], s[60:61] op_sel_hi:[1,0]
	s_mov_b32 s13, 0xa000
	v_pk_mul_f32 v[52:53], v[58:59], s[60:61] op_sel_hi:[1,0]
	v_pk_mul_f32 v[54:55], v[56:57], s[60:61] op_sel_hi:[1,0]
	v_pk_mul_f32 v[56:57], v[50:51], s[60:61] op_sel_hi:[1,0]
	v_pk_mul_f32 v[50:51], v[48:49], s[60:61] op_sel_hi:[1,0]
	v_cvt_pk_bf16_f32 v48, v54, v55
	v_cvt_pk_bf16_f32 v49, v52, v53
	v_add_co_u32_e32 v52, vcc, s89, v60
	v_cvt_pk_bf16_f32 v50, v50, v51
	v_cvt_pk_bf16_f32 v51, v56, v57
	v_pk_mul_f32 v[14:15], v[14:15], s[60:61] op_sel_hi:[1,0]
	s_nop 0
	v_addc_co_u32_e32 v53, vcc, 0, v61, vcc
	global_store_dwordx4 v[52:53], v[48:51], off offset:-4096 sc1 nt
	v_pk_mul_f32 v[4:5], v[4:5], s[60:61] op_sel_hi:[1,0]
	v_pk_mul_f32 v[6:7], v[6:7], s[60:61] op_sel_hi:[1,0]
	v_pk_mul_f32 v[48:49], v[42:43], s[60:61] op_sel_hi:[1,0]
	v_pk_mul_f32 v[42:43], v[40:41], s[60:61] op_sel_hi:[1,0]
	v_cvt_pk_bf16_f32 v40, v44, v45
	v_cvt_pk_bf16_f32 v41, v46, v47
	s_nop 0
	v_cvt_pk_bf16_f32 v42, v42, v43
	v_cvt_pk_bf16_f32 v43, v48, v49
	global_store_dwordx4 v[52:53], v[40:43], off sc1 nt
	s_nop 1
	v_pk_mul_f32 v[40:41], v[34:35], s[60:61] op_sel_hi:[1,0]
	v_pk_mul_f32 v[34:35], v[32:33], s[60:61] op_sel_hi:[1,0]
	v_cvt_pk_bf16_f32 v32, v36, v37
	v_add_co_u32_e32 v36, vcc, s23, v60
	v_cvt_pk_bf16_f32 v33, v38, v39
	v_cvt_pk_bf16_f32 v34, v34, v35
	v_cvt_pk_bf16_f32 v35, v40, v41
	s_nop 1
	v_addc_co_u32_e32 v37, vcc, 0, v61, vcc
	global_store_dwordx4 v[36:37], v[32:35], off sc1 nt
	s_nop 1
	v_pk_mul_f32 v[32:33], v[26:27], s[60:61] op_sel_hi:[1,0]
	v_pk_mul_f32 v[26:27], v[24:25], s[60:61] op_sel_hi:[1,0]
	v_cvt_pk_bf16_f32 v24, v28, v29
	v_add_co_u32_e32 v28, vcc, s72, v60
	v_cvt_pk_bf16_f32 v25, v30, v31
	v_cvt_pk_bf16_f32 v26, v26, v27
	v_cvt_pk_bf16_f32 v27, v32, v33
	s_nop 1
	v_addc_co_u32_e32 v29, vcc, 0, v61, vcc
	global_store_dwordx4 v[28:29], v[24:27], off offset:-4096 sc1 nt
	s_nop 1
	v_pk_mul_f32 v[24:25], v[18:19], s[60:61] op_sel_hi:[1,0]
	v_pk_mul_f32 v[18:19], v[16:17], s[60:61] op_sel_hi:[1,0]
	v_cvt_pk_bf16_f32 v16, v20, v21
	v_cvt_pk_bf16_f32 v17, v22, v23
	s_nop 0
	v_cvt_pk_bf16_f32 v18, v18, v19
	v_cvt_pk_bf16_f32 v19, v24, v25
	global_store_dwordx4 v[28:29], v[16:19], off sc1 nt
	s_nop 1
	v_pk_mul_f32 v[16:17], v[10:11], s[60:61] op_sel_hi:[1,0]
	v_pk_mul_f32 v[10:11], v[8:9], s[60:61] op_sel_hi:[1,0]
	v_cvt_pk_bf16_f32 v8, v12, v13
	v_add_co_u32_e32 v12, vcc, s13, v60
	v_cvt_pk_bf16_f32 v9, v14, v15
	v_cvt_pk_bf16_f32 v10, v10, v11
	v_cvt_pk_bf16_f32 v11, v16, v17
	s_nop 1
	v_addc_co_u32_e32 v13, vcc, 0, v61, vcc
	global_store_dwordx4 v[12:13], v[8:11], off sc1 nt
	s_nop 1
	v_pk_mul_f32 v[8:9], v[2:3], s[60:61] op_sel_hi:[1,0]
	v_pk_mul_f32 v[2:3], v[0:1], s[60:61] op_sel_hi:[1,0]
	v_cvt_pk_bf16_f32 v0, v4, v5
	v_add_co_u32_e32 v4, vcc, 0xb000, v60
	v_cvt_pk_bf16_f32 v1, v6, v7
	v_cvt_pk_bf16_f32 v2, v2, v3
	v_cvt_pk_bf16_f32 v3, v8, v9
	s_nop 1
	v_addc_co_u32_e32 v5, vcc, 0, v61, vcc
	global_store_dwordx4 v[4:5], v[0:3], off sc1 nt
	s_andn2_b64 vcc, exec, s[4:5]
	s_mov_b64 s[4:5], -1
	s_cbranch_vccnz .LBB0_193
